# attention: next latent unit's first K/V tiles and Q fragments prefetched at the end of the current unit's loop; prologue copies instead of loading
# baseline (speedup 1.0000x reference)
; #define LAS __attribute__((address_space(3)))
; __device__ __forceinline__ unsigned cvtpk(float lo, float hi) { f32x2 v = {lo, hi}; bf16x2_t b = __builtin_convertvector(v, bf16x2_t); return __builtin_bit_cast(unsigned, b); }
; __device__ __forceinline__ bf16_t f2bf(float f) { return (bf16_t)(cvtpk(f, 0.f) & 0xffffu); }
; __device__ __forceinline__ float bflo(unsigned u) { return __uint_as_float(u << 16); }
; __device__ __forceinline__ float bfhi(unsigned u) { return __uint_as_float(u & 0xffff0000u); }
; __device__ __forceinline__ int crow(int r, int hi) { return (r & 3) + 8 * (r >> 2) + 4 * hi; }
; __device__ __forceinline__ void attn_unit(LAS char* lds, const bf16_t* Qp, const bf16_t* KVp, const bf16_t* KRp, int ntiles, bf16_t* Yp, bool dry) {
;     ...
;     for (int k = 0; k < 4; ++k) { const f32x4 a = *(const LAS f32x4*)(wsf + 8 * k + 4 * hi);
; #pragma unroll
;         for (int j = 0; j < 4; ++j) { const int r = 4 * k + j; LAS bf16_t* op = (LAS bf16_t*)(ost + crow(r, hi) * A_OP) + r32;
;             op[0] = f2bf(o0[r] * a[j]); op[32] = f2bf(o1[r] * a[j]); } }
;     asm volatile("s_waitcnt lgkmcnt(0)" ::: "memory");
; #pragma unroll
;     for (int i = 0; i < 4; ++i) { const int id = lane + 64 * i, row = id >> 3, ch = id & 7;
;         const u32x4 ov = *(const LAS u32x4*)(ost + row * A_OP + ch * 16);
;         bf16_t* yp = Yp + (size_t)(wid * 32 + row) * ZP + ch * 8;
;         if (!dry) { const u32x4 gv = *(const u32x4*)yp; u32x4 w;
;             w.x = cvtpk(bflo(ov.x) * bflo(gv.x), bfhi(ov.x) * bfhi(gv.x)); w.y = cvtpk(bflo(ov.y) * bflo(gv.y), bfhi(ov.y) * bfhi(gv.y));
;             w.z = cvtpk(bflo(ov.z) * bflo(gv.z), bfhi(ov.z) * bfhi(gv.z)); w.w = cvtpk(bflo(ov.w) * bflo(gv.w), bfhi(ov.w) * bfhi(gv.w));
;             *(u32x4*)yp = w; } }
.Lepi_gates_done:
	s_waitcnt lgkmcnt(1)
	v_lshlrev_b32_e32 v0, 1, v198
	v_mul_u32_u24_e32 v6, 0x240, v197
	v_add3_u32 v0, s2, v0, v6
	s_waitcnt lgkmcnt(0)
	v_mul_f32_e32 v6, v34, v2
	v_mul_f32_e32 v2, v50, v2
	v_cvt_pk_bf16_f32 v2, v2, s0
	ds_write_b16 v0, v2 offset:64
	v_mul_f32_e32 v2, v35, v3
	v_cvt_pk_bf16_f32 v2, v2, s0
	ds_write_b16 v0, v2 offset:144
	v_mul_f32_e32 v2, v51, v3
	v_cvt_pk_bf16_f32 v2, v2, s0
	ds_write_b16 v0, v2 offset:208
	v_mul_f32_e32 v2, v36, v4
	v_cvt_pk_bf16_f32 v2, v2, s0
	ds_write_b16 v0, v2 offset:288
	v_mul_f32_e32 v2, v52, v4
	v_cvt_pk_bf16_f32 v2, v2, s0
	ds_write_b16 v0, v2 offset:352
	v_mul_f32_e32 v2, v37, v5
	v_cvt_pk_bf16_f32 v2, v2, s0
	ds_write_b16 v0, v2 offset:432
	v_mul_f32_e32 v2, v53, v5
	v_cvt_pk_bf16_f32 v6, v6, s0
	v_cvt_pk_bf16_f32 v2, v2, s0
	ds_write_b16 v0, v6
	ds_write_b16 v0, v2 offset:496
	ds_read_b128 v[2:5], v199 offset:32
	s_waitcnt lgkmcnt(0)
	v_mul_f32_e32 v6, v38, v2
	v_mul_f32_e32 v2, v54, v2
	v_cvt_pk_bf16_f32 v2, v2, s0
	ds_write_b16 v0, v2 offset:1216
	v_mul_f32_e32 v2, v39, v3
	v_cvt_pk_bf16_f32 v2, v2, s0
	ds_write_b16 v0, v2 offset:1296
	v_mul_f32_e32 v2, v55, v3
	v_cvt_pk_bf16_f32 v2, v2, s0
	ds_write_b16 v0, v2 offset:1360
	v_mul_f32_e32 v2, v40, v4
	v_cvt_pk_bf16_f32 v2, v2, s0
	ds_write_b16 v0, v2 offset:1440
	v_mul_f32_e32 v2, v56, v4
	v_cvt_pk_bf16_f32 v2, v2, s0
	ds_write_b16 v0, v2 offset:1504
	v_mul_f32_e32 v2, v41, v5
	v_cvt_pk_bf16_f32 v2, v2, s0
	ds_write_b16 v0, v2 offset:1584
	v_mul_f32_e32 v2, v57, v5
	v_cvt_pk_bf16_f32 v6, v6, s0
	v_cvt_pk_bf16_f32 v2, v2, s0
	ds_write_b16 v0, v6 offset:1152
	ds_write_b16 v0, v2 offset:1648
	ds_read_b128 v[2:5], v199 offset:64
	s_waitcnt lgkmcnt(0)
	v_mul_f32_e32 v6, v42, v2
	v_mul_f32_e32 v2, v58, v2
	v_cvt_pk_bf16_f32 v2, v2, s0
	ds_write_b16 v0, v2 offset:2368
	v_mul_f32_e32 v2, v43, v3
	v_cvt_pk_bf16_f32 v2, v2, s0
	ds_write_b16 v0, v2 offset:2448
	v_mul_f32_e32 v2, v59, v3
	v_cvt_pk_bf16_f32 v2, v2, s0
	ds_write_b16 v0, v2 offset:2512
	v_mul_f32_e32 v2, v44, v4
	v_cvt_pk_bf16_f32 v2, v2, s0
	ds_write_b16 v0, v2 offset:2592
	v_mul_f32_e32 v2, v60, v4
	v_cvt_pk_bf16_f32 v2, v2, s0
	ds_write_b16 v0, v2 offset:2656
	v_mul_f32_e32 v2, v45, v5
	v_cvt_pk_bf16_f32 v2, v2, s0
	ds_write_b16 v0, v2 offset:2736
	v_mul_f32_e32 v2, v61, v5
	v_cvt_pk_bf16_f32 v6, v6, s0
	v_cvt_pk_bf16_f32 v2, v2, s0
	ds_write_b16 v0, v6 offset:2304
	ds_write_b16 v0, v2 offset:2800
	ds_read_b128 v[2:5], v199 offset:96
	s_waitcnt lgkmcnt(0)
	v_mul_f32_e32 v6, v46, v2
	v_mul_f32_e32 v2, v62, v2
	v_cvt_pk_bf16_f32 v2, v2, s0
	ds_write_b16 v0, v2 offset:3520
	v_mul_f32_e32 v2, v47, v3
	v_cvt_pk_bf16_f32 v2, v2, s0
	ds_write_b16 v0, v2 offset:3600
	v_mul_f32_e32 v2, v63, v3
	v_cvt_pk_bf16_f32 v2, v2, s0
	ds_write_b16 v0, v2 offset:3664
	v_mul_f32_e32 v2, v48, v4
	v_cvt_pk_bf16_f32 v2, v2, s0
	ds_write_b16 v0, v2 offset:3744
	v_mul_f32_e32 v2, v64, v4
	v_cvt_pk_bf16_f32 v2, v2, s0
	ds_write_b16 v0, v2 offset:3808
	v_mul_f32_e32 v2, v49, v5
	v_cvt_pk_bf16_f32 v2, v2, s0
	ds_write_b16 v0, v2 offset:3888
	v_mul_f32_e32 v2, v65, v5
	v_cvt_pk_bf16_f32 v6, v6, s0
	v_cvt_pk_bf16_f32 v2, v2, s0
	ds_write_b16 v0, v6 offset:3456
	ds_write_b16 v0, v2 offset:3952
	v_lshlrev_b32_e32 v0, 1, v196
	v_lshl_add_u64 v[2:3], s[0:1], 0, v[0:1]
	s_mov_b64 s[0:1], 0x1000
	v_lshrrev_b32_e32 v0, 3, v191
	v_lshl_add_u64 v[2:3], v[2:3], 0, s[0:1]
	v_or_b32_e32 v18, s24, v0
	s_waitcnt lgkmcnt(0)
	v_mad_i64_i32 v[12:13], s[0:1], v18, s13, v[2:3]
	s_nop 0
	v_mul_u32_u24_e32 v0, 0x90, v0
	v_add3_u32 v0, s2, v188, v0
	ds_read_b128 v[4:7], v0
	s_waitcnt lgkmcnt(0)
	v_lshlrev_b32_e32 v14, 16, v4
	v_and_b32_e32 v15, 0xffff0000, v4
	s_cmp_lg_u64 s[72:73], 0
	s_cbranch_scc1 .Lepi_w10
	s_waitcnt vmcnt(0)
	s_branch .Lepi_wd
.Lepi_w10:
	s_waitcnt vmcnt(10)
; #define LAS __attribute__((address_space(3)))
; __device__ __forceinline__ unsigned cvtpk(float lo, float hi) { f32x2 v = {lo, hi}; bf16x2_t b = __builtin_convertvector(v, bf16x2_t); return __builtin_bit_cast(unsigned, b); }
; __device__ __forceinline__ float bflo(unsigned u) { return __uint_as_float(u << 16); }
; __device__ __forceinline__ float bfhi(unsigned u) { return __uint_as_float(u & 0xffff0000u); }
; __device__ __forceinline__ void attn_unit(LAS char* lds, const bf16_t* Qp, const bf16_t* KVp, const bf16_t* KRp, int ntiles, bf16_t* Yp, bool dry) {
;     ...
;     for (int i = 0; i < 4; ++i) { const int id = lane + 64 * i, row = id >> 3, ch = id & 7;
;         const u32x4 ov = *(const LAS u32x4*)(ost + row * A_OP + ch * 16);
;         bf16_t* yp = Yp + (size_t)(wid * 32 + row) * ZP + ch * 8;
;         if (!dry) { const u32x4 gv = *(const u32x4*)yp; u32x4 w;
;             w.x = cvtpk(bflo(ov.x) * bflo(gv.x), bfhi(ov.x) * bfhi(gv.x)); w.y = cvtpk(bflo(ov.y) * bflo(gv.y), bfhi(ov.y) * bfhi(gv.y));
;             w.z = cvtpk(bflo(ov.z) * bflo(gv.z), bfhi(ov.z) * bfhi(gv.z)); w.w = cvtpk(bflo(ov.w) * bflo(gv.w), bfhi(ov.w) * bfhi(gv.w));
;             *(u32x4*)yp = w; } }
.Lepi_wd:
	v_mov_b64_e32 v[8:9], v[130:131]
	v_mov_b64_e32 v[10:11], v[132:133]
	v_lshlrev_b32_e32 v16, 16, v8
	v_and_b32_e32 v17, 0xffff0000, v8
	v_pk_mul_f32 v[14:15], v[14:15], v[16:17]
	v_lshlrev_b32_e32 v8, 16, v9
	v_cvt_pk_bf16_f32 v4, v14, v15
	v_lshlrev_b32_e32 v14, 16, v5
	v_and_b32_e32 v15, 0xffff0000, v5
	v_and_b32_e32 v9, 0xffff0000, v9
	v_pk_mul_f32 v[8:9], v[14:15], v[8:9]
	v_lshlrev_b32_e32 v14, 16, v10
	v_cvt_pk_bf16_f32 v5, v8, v9
	v_lshlrev_b32_e32 v8, 16, v6
	v_and_b32_e32 v9, 0xffff0000, v6
	v_and_b32_e32 v15, 0xffff0000, v10
	v_pk_mul_f32 v[8:9], v[8:9], v[14:15]
	v_lshlrev_b32_e32 v10, 16, v11
	v_cvt_pk_bf16_f32 v6, v8, v9
	v_lshlrev_b32_e32 v8, 16, v7
	v_and_b32_e32 v9, 0xffff0000, v7
	v_and_b32_e32 v11, 0xffff0000, v11
	v_pk_mul_f32 v[8:9], v[8:9], v[10:11]
	s_nop 0
	v_cvt_pk_bf16_f32 v7, v8, v9
	global_store_dwordx4 v[12:13], v[4:7], off
	s_nop 1
	v_or_b32_e32 v4, 8, v18
	v_mad_i64_i32 v[12:13], s[0:1], v4, s13, v[2:3]
	s_nop 0
	ds_read_b128 v[4:7], v0 offset:1152
	s_waitcnt lgkmcnt(0)
	v_lshlrev_b32_e32 v14, 16, v4
	v_and_b32_e32 v15, 0xffff0000, v4
	v_mov_b64_e32 v[8:9], v[134:135]
	v_mov_b64_e32 v[10:11], v[136:137]
	v_lshlrev_b32_e32 v16, 16, v8
	v_and_b32_e32 v17, 0xffff0000, v8
	v_pk_mul_f32 v[14:15], v[14:15], v[16:17]
	v_lshlrev_b32_e32 v8, 16, v9
	v_cvt_pk_bf16_f32 v4, v14, v15
	v_lshlrev_b32_e32 v14, 16, v5
	v_and_b32_e32 v15, 0xffff0000, v5
	v_and_b32_e32 v9, 0xffff0000, v9
	v_pk_mul_f32 v[8:9], v[14:15], v[8:9]
	v_lshlrev_b32_e32 v14, 16, v10
	v_cvt_pk_bf16_f32 v5, v8, v9
	v_lshlrev_b32_e32 v8, 16, v6
	v_and_b32_e32 v9, 0xffff0000, v6
	v_and_b32_e32 v15, 0xffff0000, v10
	v_pk_mul_f32 v[8:9], v[8:9], v[14:15]
	v_lshlrev_b32_e32 v10, 16, v11
	v_cvt_pk_bf16_f32 v6, v8, v9
	v_lshlrev_b32_e32 v8, 16, v7
	v_and_b32_e32 v9, 0xffff0000, v7
	v_and_b32_e32 v11, 0xffff0000, v11
	v_pk_mul_f32 v[8:9], v[8:9], v[10:11]
	s_nop 0
	v_cvt_pk_bf16_f32 v7, v8, v9
	global_store_dwordx4 v[12:13], v[4:7], off
	s_nop 1
	v_or_b32_e32 v4, 16, v18
	v_mad_i64_i32 v[12:13], s[0:1], v4, s13, v[2:3]
	s_nop 0
	ds_read_b128 v[4:7], v0 offset:2304
	s_waitcnt lgkmcnt(0)
	v_lshlrev_b32_e32 v14, 16, v4
	v_and_b32_e32 v15, 0xffff0000, v4
	v_mov_b64_e32 v[8:9], v[138:139]
	v_mov_b64_e32 v[10:11], v[140:141]
	v_lshlrev_b32_e32 v16, 16, v8
	v_and_b32_e32 v17, 0xffff0000, v8
	v_pk_mul_f32 v[14:15], v[14:15], v[16:17]
	v_lshlrev_b32_e32 v8, 16, v9
	v_cvt_pk_bf16_f32 v4, v14, v15
	v_lshlrev_b32_e32 v14, 16, v5
	v_and_b32_e32 v15, 0xffff0000, v5
	v_and_b32_e32 v9, 0xffff0000, v9
	v_pk_mul_f32 v[8:9], v[14:15], v[8:9]
	v_lshlrev_b32_e32 v14, 16, v10
	v_cvt_pk_bf16_f32 v5, v8, v9
	v_lshlrev_b32_e32 v8, 16, v6
	v_and_b32_e32 v9, 0xffff0000, v6
	v_and_b32_e32 v15, 0xffff0000, v10
	v_pk_mul_f32 v[8:9], v[8:9], v[14:15]
	v_lshlrev_b32_e32 v10, 16, v11
	v_cvt_pk_bf16_f32 v6, v8, v9
	v_lshlrev_b32_e32 v8, 16, v7
	v_and_b32_e32 v9, 0xffff0000, v7
	v_and_b32_e32 v11, 0xffff0000, v11
	v_pk_mul_f32 v[8:9], v[8:9], v[10:11]
	s_nop 0
	v_cvt_pk_bf16_f32 v7, v8, v9
	global_store_dwordx4 v[12:13], v[4:7], off
	s_nop 1
	v_or_b32_e32 v4, 24, v18
	v_mad_i64_i32 v[10:11], s[0:1], v4, s13, v[2:3]
	s_nop 0
	ds_read_b128 v[2:5], v0 offset:3456
	s_waitcnt lgkmcnt(0)
	v_lshlrev_b32_e32 v12, 16, v2
	v_and_b32_e32 v13, 0xffff0000, v2
	v_mov_b64_e32 v[6:7], v[142:143]
	v_mov_b64_e32 v[8:9], v[144:145]
	v_lshlrev_b32_e32 v14, 16, v6
	v_and_b32_e32 v15, 0xffff0000, v6
	v_pk_mul_f32 v[12:13], v[12:13], v[14:15]
	v_lshlrev_b32_e32 v6, 16, v7
	v_cvt_pk_bf16_f32 v2, v12, v13
	v_lshlrev_b32_e32 v12, 16, v3
	v_and_b32_e32 v13, 0xffff0000, v3
	v_and_b32_e32 v7, 0xffff0000, v7
	v_pk_mul_f32 v[6:7], v[12:13], v[6:7]
	v_lshlrev_b32_e32 v12, 16, v8
	v_cvt_pk_bf16_f32 v3, v6, v7
	v_lshlrev_b32_e32 v6, 16, v4
	v_and_b32_e32 v7, 0xffff0000, v4
	v_and_b32_e32 v13, 0xffff0000, v8
	v_pk_mul_f32 v[6:7], v[6:7], v[12:13]
	v_lshlrev_b32_e32 v8, 16, v9
	v_cvt_pk_bf16_f32 v4, v6, v7
	v_lshlrev_b32_e32 v6, 16, v5
	v_and_b32_e32 v7, 0xffff0000, v5
	v_and_b32_e32 v9, 0xffff0000, v9
	v_pk_mul_f32 v[6:7], v[6:7], v[8:9]
	s_nop 0
	v_cvt_pk_bf16_f32 v5, v6, v7
	global_store_dwordx4 v[10:11], v[2:5], off
	s_barrier

; #define AT_LOAD(X, t) do { const size_t adv_ = (size_t)(t) * 64; sk##X = *(const u32x4*)(gk + adv_ * 1024); sv##X = *(const u32x4*)(gv + adv_ * 1024); if (rth) sr##X = *(const u32x4*)(gr + adv_ * 32); } while (0)
; #define AT_STORE(X, slot) do { *(LAS u32x4*)(lds + A_K0 + (slot) * AK_BYTES + lk) = sk##X; *(LAS u32x4*)(lds + A_V0 + (slot) * AV_BYTES + lv) = sv##X; if (rth) *(LAS u32x4*)(lds + A_K0 + (slot) * AK_BYTES + lr) = sr##X; } while (0)
; __device__ __forceinline__ void attn_unit(LAS char* lds, const bf16_t* Qp, const bf16_t* KVp, const bf16_t* KRp, int ntiles, bf16_t* Yp, bool dry) {
;     ...
;     const int krow = tid >> 3, kc = tid & 7, rrow = tid >> 2, rc = tid & 3;
;     const bf16_t* gk = KVp + (size_t)krow * 1024 + kc * 8;
;     const bf16_t* gv = gk + 512;
;     const bf16_t* gr = KRp + (size_t)rrow * 32 + rc * 8;
;     const int lk = krow * AK_PITCH + kc * 16, lr = rrow * AK_PITCH + 128 + rc * 16, lv = (kc >> 2) * 4096 + krow * 64 + (kc & 3) * 16;
;     const bool rth = tid < 256;
;     u32x4 skA, svA, srA = {0u, 0u, 0u, 0u}, skB, svB, srB = {0u, 0u, 0u, 0u};
;     ...
;     AT_LOAD(A, 0); AT_LOAD(B, 1);
;     bf16x8 qf[6];
;     { const bf16_t* qrow = Qp + (size_t)(wid * 32 + r32) * 768;
; #pragma unroll
;       for (int s = 0; s < 6; ++s) qf[s] = *(const bf16x8*)(qrow + 16 * s + 8 * hi); }
;     AT_STORE(A, 0); AT_STORE(B, 1);
.LBB0_822:
	s_and_b64 vcc, exec, s[0:1]
	s_cbranch_vccz .LBB0_782
	v_readlane_b32 s72, v252, 4
	s_cmp_lg_u32 s8, s72
	s_cselect_b64 s[72:73], -1, 0
	s_ashr_i32 s24, s8, 6
	s_bfe_u32 s34, s8, 0x30003
	s_mul_i32 s17, s24, 0x480000
	s_mul_hi_i32 s16, s24, 0x480000
	s_add_u32 s0, s76, s17
	v_mov_b32_e32 v16, v182
	s_addc_u32 s1, s77, s16
	s_lshl_b32 s2, s34, 7
	s_add_u32 s0, s0, s2
	v_ashrrev_i32_e32 v8, 3, v16
	v_ashrrev_i32_e32 v9, 31, v8
	s_addc_u32 s1, s1, 0
	v_and_b32_e32 v17, 7, v16
	v_lshlrev_b64 v[2:3], 11, v[8:9]
	v_lshl_add_u64 v[4:5], s[0:1], 0, v[2:3]
	v_lshlrev_b32_e32 v188, 4, v17
	v_mov_b32_e32 v189, v1
	v_lshl_add_u64 v[12:13], v[4:5], 0, v[188:189]
	s_cmp_lg_u64 s[72:73], 0
	s_cbranch_scc1 .Lpf_s1
	global_load_dwordx4 v[130:133], v[12:13], off
	global_load_dwordx4 v[134:137], v[12:13], off offset:1024
.Lpf_s1:
	s_mul_i32 s2, s24, 0x24000
	v_ashrrev_i32_e32 v10, 2, v16
	s_mul_hi_i32 s3, s24, 0x24000
	s_add_u32 s0, s64, s2
	v_ashrrev_i32_e32 v11, 31, v10
	s_addc_u32 s1, s65, s3
	v_and_b32_e32 v0, 3, v16
	v_lshlrev_b64 v[6:7], 6, v[10:11]
	v_mov_b32_e32 v142, v1
	v_mov_b32_e32 v143, v1
	v_lshl_add_u64 v[14:15], s[0:1], 0, v[6:7]
	v_lshlrev_b32_e32 v4, 4, v0
	v_mov_b32_e32 v5, v1
	s_movk_i32 s0, 0xff
	s_movk_i32 s14, 0x100
	v_mov_b32_e32 v144, v1
	v_mov_b32_e32 v145, v1
	v_mov_b64_e32 v[138:139], v[142:143]
	v_readfirstlane_b32 s35, v16
	v_lshl_add_u64 v[14:15], v[14:15], 0, v[4:5]
	v_cmp_lt_i32_e64 s[0:1], s0, v16
	v_cmp_gt_i32_e64 s[38:39], s14, v16
	v_mov_b64_e32 v[140:141], v[144:145]
	s_and_saveexec_b64 s[14:15], s[38:39]
	s_cbranch_execz .LBB0_825
	s_cmp_lg_u64 s[72:73], 0
	s_cbranch_scc1 .Lpf_s2
	global_load_dwordx4 v[138:141], v[14:15], off
.Lpf_s2:
.LBB0_825:
	s_or_b64 exec, exec, s[14:15]
	v_add_co_u32_e32 v12, vcc, 0x20000, v12
	s_nop 1
	v_addc_co_u32_e32 v13, vcc, 0, v13, vcc
	s_cmp_lg_u64 s[72:73], 0
	s_cbranch_scc1 .Lpf_s3
	global_load_dwordx4 v[146:149], v[12:13], off
	global_load_dwordx4 v[150:153], v[12:13], off offset:1024
.Lpf_s3:
	s_and_saveexec_b64 s[14:15], s[38:39]
	s_cbranch_execz .LBB0_827
	v_add_co_u32_e32 v12, vcc, 0x1000, v14
	s_nop 1
	v_addc_co_u32_e32 v13, vcc, 0, v15, vcc
	s_cmp_lg_u64 s[72:73], 0
	s_cbranch_scc1 .Lpf_s4
	global_load_dwordx4 v[142:145], v[12:13], off
.Lpf_s4:
.LBB0_827:
	s_or_b64 exec, exec, s[14:15]
	s_lshl_b32 s15, s8, 8
	s_mul_hi_i32 s14, s24, 0x900
	s_mulk_i32 s24, 0x900
	s_and_b32 s15, s15, 0x700
	s_add_u32 s15, s24, s15
	s_addc_u32 s14, s14, 0
	s_add_u32 s25, s15, 0x100
	s_addc_u32 s28, s14, 0
	s_mul_i32 s14, s28, 0x600
	s_mul_hi_u32 s15, s25, 0x600
	s_add_i32 s15, s15, s14
	s_mul_i32 s14, s25, 0x600
	v_readlane_b32 s40, v252, 11
	v_readlane_b32 s41, v252, 12
	s_add_u32 s14, s40, s14
	s_addc_u32 s15, s41, s15
	s_mul_i32 s24, s34, 0xc0
	s_add_u32 s14, s14, s24
	s_addc_u32 s15, s15, 0
	s_ashr_i32 s29, s35, 6
	v_and_b32_e32 v198, 31, v16
	s_lshl_b32 s24, s29, 5
	v_bfe_u32 v197, v16, 5, 1
	v_or_b32_e32 v0, s24, v198
	v_mov_b64_e32 v[12:13], s[14:15]
	s_movk_i32 s14, 0x600
	v_mad_i64_i32 v[12:13], s[14:15], v0, s14, v[12:13]
	v_lshlrev_b32_e32 v0, 4, v197
	v_lshl_add_u64 v[12:13], v[12:13], 0, v[0:1]
	s_cmp_lg_u64 s[72:73], 0
	s_cbranch_scc1 .Lpf_s5
	global_load_dwordx4 v[154:157], v[12:13], off
	global_load_dwordx4 v[158:161], v[12:13], off offset:32
	global_load_dwordx4 v[162:165], v[12:13], off offset:64
	global_load_dwordx4 v[166:169], v[12:13], off offset:96
	global_load_dwordx4 v[170:173], v[12:13], off offset:128
	global_load_dwordx4 v[174:177], v[12:13], off offset:160
.Lpf_s5:
	v_lshlrev_b32_e32 v5, 10, v17
	s_movk_i32 s40, 0xd0
	v_and_b32_e32 v5, 0x1000, v5
	v_mad_u64_u32 v[190:191], s[14:15], v8, s40, v[188:189]
	v_lshl_add_u32 v8, v8, 6, v5
	v_lshlrev_b32_e32 v5, 4, v16
	v_mul_lo_u32 v9, v10, s40
	v_and_or_b32 v8, v5, 48, v8
	v_add_u32_e32 v200, 0, v190
	v_add_u32_e32 v201, 0, v8
	v_add_u32_e32 v206, v9, v4
	s_cmp_lg_u64 s[72:73], 0
	s_cbranch_scc0 .Lpf_nocopy
	s_waitcnt vmcnt(0)
	v_mov_b64_e32 v[130:131], v[66:67]
	v_mov_b64_e32 v[132:133], v[68:69]
	v_mov_b64_e32 v[134:135], v[70:71]
	v_mov_b64_e32 v[136:137], v[72:73]
	v_mov_b64_e32 v[138:139], v[74:75]
	v_mov_b64_e32 v[140:141], v[76:77]
	v_mov_b64_e32 v[146:147], v[78:79]
	v_mov_b64_e32 v[148:149], v[80:81]
	v_mov_b64_e32 v[150:151], v[82:83]
	v_mov_b64_e32 v[152:153], v[84:85]
	v_mov_b64_e32 v[142:143], v[86:87]
	v_mov_b64_e32 v[144:145], v[88:89]
.Lpf_nocopy:
	s_waitcnt vmcnt(9)
	ds_write_b128 v200, v[130:133]
	s_waitcnt vmcnt(8)
	ds_write_b128 v201, v[134:137] offset:53248
	s_and_saveexec_b64 s[14:15], s[0:1]
	s_xor_b64 s[14:15], exec, s[14:15]
	s_cbranch_execz .LBB0_829
	s_waitcnt vmcnt(7)
	ds_write_b128 v200, v[146:149] offset:13312
	s_waitcnt vmcnt(6)
	ds_write_b128 v201, v[150:153] offset:61440
	v_add_u32_e32 v206, v9, v4

; #define AT_LOAD(X, t) do { const size_t adv_ = (size_t)(t) * 64; sk##X = *(const u32x4*)(gk + adv_ * 1024); sv##X = *(const u32x4*)(gv + adv_ * 1024); if (rth) sr##X = *(const u32x4*)(gr + adv_ * 32); } while (0)
; __device__ __forceinline__ void attn_unit(LAS char* lds, const bf16_t* Qp, const bf16_t* KVp, const bf16_t* KRp, int ntiles, bf16_t* Yp, bool dry) {
;     ...
;     AT_LOAD(A, 0); AT_LOAD(B, 1);
;     bf16x8 qf[6];
;     { const bf16_t* qrow = Qp + (size_t)(wid * 32 + r32) * 768;
; #pragma unroll
;       for (int s = 0; s < 6; ++s) qf[s] = *(const bf16x8*)(qrow + 16 * s + 8 * hi); }
.Latt_latch:
	s_add_i32 s35, s35, 2
	v_lshl_add_u64 v[192:193], v[192:193], 0, s[60:61]
	v_lshl_add_u64 v[194:195], v[194:195], 0, s[26:27]
	s_waitcnt lgkmcnt(0)
	s_barrier
	s_cmp_lt_u32 s35, 36
	s_cbranch_scc1 .Latt_loop
	v_readlane_b32 s2, v252, 0
	s_mov_b64 s[72:73], 0
	s_add_i32 s2, s8, s2
	s_cmpk_gt_i32 s2, 0x7ff
	s_cbranch_scc1 .Latt_nopf
	s_cmp_ge_i32 s2, s69
	s_cbranch_scc1 .Latt_nopf
	s_mov_b64 s[72:73], -1
	v_lshl_add_u64 v[180:181], s[88:89], 0, v[192:193]
	s_and_saveexec_b64 s[16:17], s[38:39]
	s_cbranch_execz .Latt_pf1
	v_add_co_u32_e32 v184, vcc, 0x3cc6c000, v180
	s_nop 1
	v_addc_co_u32_e32 v185, vcc, 0, v181, vcc
	global_load_dwordx4 v[74:77], v[184:185], off
	v_add_co_u32_e32 v180, vcc, 0x3cc6d000, v180
	s_nop 1
	v_addc_co_u32_e32 v181, vcc, 0, v181, vcc
	global_load_dwordx4 v[86:89], v[180:181], off
.Latt_pf1:
	s_or_b64 exec, exec, s[16:17]
	v_lshl_add_u64 v[178:179], s[88:89], 0, v[194:195]
	v_add_co_u32_e32 v180, vcc, 0x30180000, v178
	s_nop 1
	v_addc_co_u32_e32 v181, vcc, 0, v179, vcc
	global_load_dwordx4 v[66:69], v[180:181], off
	global_load_dwordx4 v[70:73], v[180:181], off offset:1024
	v_add_co_u32_e32 v178, vcc, 0x301a0000, v178
	s_nop 1
	v_addc_co_u32_e32 v179, vcc, 0, v179, vcc
	global_load_dwordx4 v[78:81], v[178:179], off
	global_load_dwordx4 v[82:85], v[178:179], off offset:1024
	s_ashr_i32 s14, s8, 6
	s_mul_i32 s14, s14, 0x900
	s_lshl_b32 s15, s8, 8
	s_and_b32 s15, s15, 0x700
	s_add_i32 s14, s14, s15
	s_addk_i32 s14, 0x100
	s_mul_i32 s14, s14, 0x600
	s_bfe_u32 s15, s8, 0x30003
	s_mul_i32 s15, s15, 0xc0
	s_add_i32 s14, s14, s15
	s_add_i32 s14, s14, 0xd80000
	v_readlane_b32 s16, v252, 11
	v_readlane_b32 s17, v252, 12
	s_add_u32 s16, s16, s14
	s_addc_u32 s17, s17, 0
	s_lshl_b32 s15, s29, 5
	v_or_b32_e32 v178, s15, v198
	v_mul_u32_u24_e32 v178, 0x600, v178
	v_lshl_add_u32 v178, v197, 4, v178
	v_mov_b32_e32 v179, 0
	v_lshl_add_u64 v[180:181], s[16:17], 0, v[178:179]
	global_load_dwordx4 v[154:157], v[180:181], off
	global_load_dwordx4 v[158:161], v[180:181], off offset:32
	global_load_dwordx4 v[162:165], v[180:181], off offset:64
	global_load_dwordx4 v[166:169], v[180:181], off offset:96
	global_load_dwordx4 v[170:173], v[180:181], off offset:128
	global_load_dwordx4 v[174:177], v[180:181], off offset:160
.Latt_nopf:
	v_and_b32_e32 v3, 64, v203
	v_xor_b32_e32 v2, 32, v203
	v_add_u32_e32 v3, 64, v3
	v_cmp_lt_i32_e32 vcc, v2, v3
	s_nop 1
	v_cndmask_b32_e32 v2, v203, v2, vcc
	v_lshlrev_b32_e32 v98, 2, v2
	s_branch .LBB0_858
